# P2b S5 chunk-prefix loop software-pipelined (loads one trip ahead, counted vmcnt) on top of batched P2b conversion
# baseline (speedup 1.0000x reference)
.LBB0_438:
	s_nop 0
	v_ashrrev_i32_e32 v0, 6, v26
	v_add_u32_e32 v2, s71, v0
	s_movk_i32 s0, 0x80
	v_cmp_gt_i32_e32 vcc, s0, v2
	s_and_saveexec_b64 s[0:1], vcc
	s_cbranch_execz .LBB0_441
	v_ashrrev_i32_e32 v0, 1, v2
	v_and_b32_e32 v0, 0xffffffe0, v0
	v_lshl_add_u32 v0, s45, 6, v0
	v_and_or_b32 v0, v2, 31, v0
	v_ashrrev_i32_e32 v1, 31, v0
	v_and_b32_e32 v4, 63, v26
	v_lshlrev_b64 v[0:1], 10, v[0:1]
	v_lshl_add_u64 v[0:1], s[2:3], 0, v[0:1]
	v_lshlrev_b32_e32 v112, 4, v4
	v_lshl_add_u64 v[0:1], v[0:1], 0, v[112:113]
	v_add_co_u32_e32 v0, vcc, 0x80000, v0
	s_mov_b32 s4, 0x10800
	s_nop 0
	v_addc_co_u32_e32 v1, vcc, 0, v1, vcc
	global_load_dwordx2 v[0:1], v[0:1], off offset:8
	v_mad_i64_i32 v[2:3], s[4:5], v2, s4, 0
	v_lshl_or_b32 v2, v4, 2, v2
	v_mov_b32_e32 v6, 0
	v_lshl_add_u64 v[2:3], s[2:3], 0, v[2:3]
	s_mov_b64 s[2:3], 0x19e01700
	s_mov_b32 s4, -12
	v_lshl_add_u64 v[2:3], v[2:3], 0, s[2:3]
	v_mov_b32_e32 v7, v6
	s_waitcnt vmcnt(0) lgkmcnt(0)
	v_pk_mov_b32 v[4:5], v[0:1], v[0:1] op_sel:[1,0]
	s_mov_b32 s2, 0xfffff400
	s_mov_b32 s3, -1
	v_lshl_add_u64 v[2:3], v[2:3], 0, s[2:3]
	s_mov_b64 s[2:3], 0x1800
	s_movk_i32 s4, 4
	global_load_dword v16, v[2:3], off offset:-2816
	global_load_dword v17, v[2:3], off offset:-2560
	global_load_dword v18, v[2:3], off offset:-2304
	global_load_dword v19, v[2:3], off offset:-2048
	global_load_dword v20, v[2:3], off offset:-1792
	global_load_dword v21, v[2:3], off offset:-1536
	global_load_dword v22, v[2:3], off offset:-1280
	global_load_dword v23, v[2:3], off offset:-1024
	global_load_dword v24, v[2:3], off offset:-768
	global_load_dword v25, v[2:3], off offset:-512
	global_load_dword v26, v[2:3], off offset:-256
	global_load_dword v27, v[2:3], off offset:0
	global_load_dword v28, v[2:3], off offset:256
	global_load_dword v29, v[2:3], off offset:512
	global_load_dword v30, v[2:3], off offset:768
	global_load_dword v31, v[2:3], off offset:1024
	global_load_dword v32, v[2:3], off offset:1280
	global_load_dword v33, v[2:3], off offset:1536
	global_load_dword v34, v[2:3], off offset:1792
	global_load_dword v35, v[2:3], off offset:2048
	global_load_dword v36, v[2:3], off offset:2304
	global_load_dword v37, v[2:3], off offset:2560
	global_load_dword v38, v[2:3], off offset:2816
	global_load_dword v39, v[2:3], off offset:3072
	v_lshl_add_u64 v[8:9], v[2:3], 0, s[2:3]
	global_load_dword v40, v[8:9], off offset:-2816
	global_load_dword v41, v[8:9], off offset:-2560
	global_load_dword v42, v[8:9], off offset:-2304
	global_load_dword v43, v[8:9], off offset:-2048
	global_load_dword v44, v[8:9], off offset:-1792
	global_load_dword v45, v[8:9], off offset:-1536
	global_load_dword v46, v[8:9], off offset:-1280
	global_load_dword v47, v[8:9], off offset:-1024
	global_load_dword v48, v[8:9], off offset:-768
	global_load_dword v49, v[8:9], off offset:-512
	global_load_dword v50, v[8:9], off offset:-256
	global_load_dword v51, v[8:9], off offset:0
	global_load_dword v52, v[8:9], off offset:256
	global_load_dword v53, v[8:9], off offset:512
	global_load_dword v54, v[8:9], off offset:768
	global_load_dword v55, v[8:9], off offset:1024
	global_load_dword v56, v[8:9], off offset:1280
	global_load_dword v57, v[8:9], off offset:1536
	global_load_dword v58, v[8:9], off offset:1792
	global_load_dword v59, v[8:9], off offset:2048
	global_load_dword v60, v[8:9], off offset:2304
	global_load_dword v61, v[8:9], off offset:2560
	global_load_dword v62, v[8:9], off offset:2816
	global_load_dword v63, v[8:9], off offset:3072
	s_waitcnt vmcnt(24)
	global_store_dword v[2:3], v6, off offset:-2816
	global_store_dword v[2:3], v7, off offset:-2560
	v_mul_f32_e32 v10, v1, v7
	v_mul_f32_e32 v11, v1, v6
	v_fma_f32 v12, v0, v6, -v10
	v_fma_f32 v13, v0, v7, v11
	v_add_f32_e32 v14, v12, v16
	v_add_f32_e32 v15, v13, v17
	global_store_dword v[2:3], v14, off offset:-2304
	global_store_dword v[2:3], v15, off offset:-2048
	v_mul_f32_e32 v10, v1, v15
	v_mul_f32_e32 v11, v1, v14
	v_fma_f32 v12, v0, v14, -v10
	v_fma_f32 v13, v0, v15, v11
	v_add_f32_e32 v6, v12, v18
	v_add_f32_e32 v7, v13, v19
	global_store_dword v[2:3], v6, off offset:-1792
	global_store_dword v[2:3], v7, off offset:-1536
	v_mul_f32_e32 v10, v1, v7
	v_mul_f32_e32 v11, v1, v6
	v_fma_f32 v12, v0, v6, -v10
	v_fma_f32 v13, v0, v7, v11
	v_add_f32_e32 v14, v12, v20
	v_add_f32_e32 v15, v13, v21
	global_store_dword v[2:3], v14, off offset:-1280
	global_store_dword v[2:3], v15, off offset:-1024
	v_mul_f32_e32 v10, v1, v15
	v_mul_f32_e32 v11, v1, v14
	v_fma_f32 v12, v0, v14, -v10
	v_fma_f32 v13, v0, v15, v11
	v_add_f32_e32 v6, v12, v22
	v_add_f32_e32 v7, v13, v23
	global_store_dword v[2:3], v6, off offset:-768
	global_store_dword v[2:3], v7, off offset:-512
	v_mul_f32_e32 v10, v1, v7
	v_mul_f32_e32 v11, v1, v6
	v_fma_f32 v12, v0, v6, -v10
	v_fma_f32 v13, v0, v7, v11
	v_add_f32_e32 v14, v12, v24
	v_add_f32_e32 v15, v13, v25
	global_store_dword v[2:3], v14, off offset:-256
	global_store_dword v[2:3], v15, off offset:0
	v_mul_f32_e32 v10, v1, v15
	v_mul_f32_e32 v11, v1, v14
	v_fma_f32 v12, v0, v14, -v10
	v_fma_f32 v13, v0, v15, v11
	v_add_f32_e32 v6, v12, v26
	v_add_f32_e32 v7, v13, v27
	global_store_dword v[2:3], v6, off offset:256
	global_store_dword v[2:3], v7, off offset:512
	v_mul_f32_e32 v10, v1, v7
	v_mul_f32_e32 v11, v1, v6
	v_fma_f32 v12, v0, v6, -v10
	v_fma_f32 v13, v0, v7, v11
	v_add_f32_e32 v14, v12, v28
	v_add_f32_e32 v15, v13, v29
	global_store_dword v[2:3], v14, off offset:768
	global_store_dword v[2:3], v15, off offset:1024
	v_mul_f32_e32 v10, v1, v15
	v_mul_f32_e32 v11, v1, v14
	v_fma_f32 v12, v0, v14, -v10
	v_fma_f32 v13, v0, v15, v11
	v_add_f32_e32 v6, v12, v30
	v_add_f32_e32 v7, v13, v31
	global_store_dword v[2:3], v6, off offset:1280
	global_store_dword v[2:3], v7, off offset:1536
	v_mul_f32_e32 v10, v1, v7
	v_mul_f32_e32 v11, v1, v6
	v_fma_f32 v12, v0, v6, -v10
	v_fma_f32 v13, v0, v7, v11
	v_add_f32_e32 v14, v12, v32
	v_add_f32_e32 v15, v13, v33
	global_store_dword v[2:3], v14, off offset:1792
	global_store_dword v[2:3], v15, off offset:2048
	v_mul_f32_e32 v10, v1, v15
	v_mul_f32_e32 v11, v1, v14
	v_fma_f32 v12, v0, v14, -v10
	v_fma_f32 v13, v0, v15, v11
	v_add_f32_e32 v6, v12, v34
	v_add_f32_e32 v7, v13, v35
	global_store_dword v[2:3], v6, off offset:2304
	global_store_dword v[2:3], v7, off offset:2560
	v_mul_f32_e32 v10, v1, v7
	v_mul_f32_e32 v11, v1, v6
	v_fma_f32 v12, v0, v6, -v10
	v_fma_f32 v13, v0, v7, v11
	v_add_f32_e32 v14, v12, v36
	v_add_f32_e32 v15, v13, v37
	global_store_dword v[2:3], v14, off offset:2816
	global_store_dword v[2:3], v15, off offset:3072
	v_mul_f32_e32 v10, v1, v15
	v_mul_f32_e32 v11, v1, v14
	v_fma_f32 v12, v0, v14, -v10
	v_fma_f32 v13, v0, v15, v11
	v_add_f32_e32 v6, v12, v38
	v_add_f32_e32 v7, v13, v39
.Lpfx_loop:
	v_lshl_add_u64 v[2:3], v[8:9], 0, s[2:3]
	global_load_dword v16, v[2:3], off offset:-2816
	global_load_dword v17, v[2:3], off offset:-2560
	global_load_dword v18, v[2:3], off offset:-2304
	global_load_dword v19, v[2:3], off offset:-2048
	global_load_dword v20, v[2:3], off offset:-1792
	global_load_dword v21, v[2:3], off offset:-1536
	global_load_dword v22, v[2:3], off offset:-1280
	global_load_dword v23, v[2:3], off offset:-1024
	global_load_dword v24, v[2:3], off offset:-768
	global_load_dword v25, v[2:3], off offset:-512
	global_load_dword v26, v[2:3], off offset:-256
	global_load_dword v27, v[2:3], off offset:0
	global_load_dword v28, v[2:3], off offset:256
	global_load_dword v29, v[2:3], off offset:512
	global_load_dword v30, v[2:3], off offset:768
	global_load_dword v31, v[2:3], off offset:1024
	global_load_dword v32, v[2:3], off offset:1280
	global_load_dword v33, v[2:3], off offset:1536
	global_load_dword v34, v[2:3], off offset:1792
	global_load_dword v35, v[2:3], off offset:2048
	global_load_dword v36, v[2:3], off offset:2304
	global_load_dword v37, v[2:3], off offset:2560
	global_load_dword v38, v[2:3], off offset:2816
	global_load_dword v39, v[2:3], off offset:3072
	s_waitcnt vmcnt(48)
	global_store_dword v[8:9], v6, off offset:-2816
	global_store_dword v[8:9], v7, off offset:-2560
	v_mul_f32_e32 v10, v1, v7
	v_mul_f32_e32 v11, v1, v6
	v_fma_f32 v12, v0, v6, -v10
	v_fma_f32 v13, v0, v7, v11
	v_add_f32_e32 v14, v12, v40
	v_add_f32_e32 v15, v13, v41
	global_store_dword v[8:9], v14, off offset:-2304
	global_store_dword v[8:9], v15, off offset:-2048
	v_mul_f32_e32 v10, v1, v15
	v_mul_f32_e32 v11, v1, v14
	v_fma_f32 v12, v0, v14, -v10
	v_fma_f32 v13, v0, v15, v11
	v_add_f32_e32 v6, v12, v42
	v_add_f32_e32 v7, v13, v43
	global_store_dword v[8:9], v6, off offset:-1792
	global_store_dword v[8:9], v7, off offset:-1536
	v_mul_f32_e32 v10, v1, v7
	v_mul_f32_e32 v11, v1, v6
	v_fma_f32 v12, v0, v6, -v10
	v_fma_f32 v13, v0, v7, v11
	v_add_f32_e32 v14, v12, v44
	v_add_f32_e32 v15, v13, v45
	global_store_dword v[8:9], v14, off offset:-1280
	global_store_dword v[8:9], v15, off offset:-1024
	v_mul_f32_e32 v10, v1, v15
	v_mul_f32_e32 v11, v1, v14
	v_fma_f32 v12, v0, v14, -v10
	v_fma_f32 v13, v0, v15, v11
	v_add_f32_e32 v6, v12, v46
	v_add_f32_e32 v7, v13, v47
	global_store_dword v[8:9], v6, off offset:-768
	global_store_dword v[8:9], v7, off offset:-512
	v_mul_f32_e32 v10, v1, v7
	v_mul_f32_e32 v11, v1, v6
	v_fma_f32 v12, v0, v6, -v10
	v_fma_f32 v13, v0, v7, v11
	v_add_f32_e32 v14, v12, v48
	v_add_f32_e32 v15, v13, v49
	global_store_dword v[8:9], v14, off offset:-256
	global_store_dword v[8:9], v15, off offset:0
	v_mul_f32_e32 v10, v1, v15
	v_mul_f32_e32 v11, v1, v14
	v_fma_f32 v12, v0, v14, -v10
	v_fma_f32 v13, v0, v15, v11
	v_add_f32_e32 v6, v12, v50
	v_add_f32_e32 v7, v13, v51
	global_store_dword v[8:9], v6, off offset:256
	global_store_dword v[8:9], v7, off offset:512
	v_mul_f32_e32 v10, v1, v7
	v_mul_f32_e32 v11, v1, v6
	v_fma_f32 v12, v0, v6, -v10
	v_fma_f32 v13, v0, v7, v11
	v_add_f32_e32 v14, v12, v52
	v_add_f32_e32 v15, v13, v53
	global_store_dword v[8:9], v14, off offset:768
	global_store_dword v[8:9], v15, off offset:1024
	v_mul_f32_e32 v10, v1, v15
	v_mul_f32_e32 v11, v1, v14
	v_fma_f32 v12, v0, v14, -v10
	v_fma_f32 v13, v0, v15, v11
	v_add_f32_e32 v6, v12, v54
	v_add_f32_e32 v7, v13, v55
	global_store_dword v[8:9], v6, off offset:1280
	global_store_dword v[8:9], v7, off offset:1536
	v_mul_f32_e32 v10, v1, v7
	v_mul_f32_e32 v11, v1, v6
	v_fma_f32 v12, v0, v6, -v10
	v_fma_f32 v13, v0, v7, v11
	v_add_f32_e32 v14, v12, v56
	v_add_f32_e32 v15, v13, v57
	global_store_dword v[8:9], v14, off offset:1792
	global_store_dword v[8:9], v15, off offset:2048
	v_mul_f32_e32 v10, v1, v15
	v_mul_f32_e32 v11, v1, v14
	v_fma_f32 v12, v0, v14, -v10
	v_fma_f32 v13, v0, v15, v11
	v_add_f32_e32 v6, v12, v58
	v_add_f32_e32 v7, v13, v59
	global_store_dword v[8:9], v6, off offset:2304
	global_store_dword v[8:9], v7, off offset:2560
	v_mul_f32_e32 v10, v1, v7
	v_mul_f32_e32 v11, v1, v6
	v_fma_f32 v12, v0, v6, -v10
	v_fma_f32 v13, v0, v7, v11
	v_add_f32_e32 v14, v12, v60
	v_add_f32_e32 v15, v13, v61
	global_store_dword v[8:9], v14, off offset:2816
	global_store_dword v[8:9], v15, off offset:3072
	v_mul_f32_e32 v10, v1, v15
	v_mul_f32_e32 v11, v1, v14
	v_fma_f32 v12, v0, v14, -v10
	v_fma_f32 v13, v0, v15, v11
	v_add_f32_e32 v6, v12, v62
	v_add_f32_e32 v7, v13, v63
	v_lshl_add_u64 v[8:9], v[2:3], 0, s[2:3]
	global_load_dword v40, v[8:9], off offset:-2816
	global_load_dword v41, v[8:9], off offset:-2560
	global_load_dword v42, v[8:9], off offset:-2304
	global_load_dword v43, v[8:9], off offset:-2048
	global_load_dword v44, v[8:9], off offset:-1792
	global_load_dword v45, v[8:9], off offset:-1536
	global_load_dword v46, v[8:9], off offset:-1280
	global_load_dword v47, v[8:9], off offset:-1024
	global_load_dword v48, v[8:9], off offset:-768
	global_load_dword v49, v[8:9], off offset:-512
	global_load_dword v50, v[8:9], off offset:-256
	global_load_dword v51, v[8:9], off offset:0
	global_load_dword v52, v[8:9], off offset:256
	global_load_dword v53, v[8:9], off offset:512
	global_load_dword v54, v[8:9], off offset:768
	global_load_dword v55, v[8:9], off offset:1024
	global_load_dword v56, v[8:9], off offset:1280
	global_load_dword v57, v[8:9], off offset:1536
	global_load_dword v58, v[8:9], off offset:1792
	global_load_dword v59, v[8:9], off offset:2048
	global_load_dword v60, v[8:9], off offset:2304
	global_load_dword v61, v[8:9], off offset:2560
	global_load_dword v62, v[8:9], off offset:2816
	global_load_dword v63, v[8:9], off offset:3072
	s_waitcnt vmcnt(48)
	global_store_dword v[2:3], v6, off offset:-2816
	global_store_dword v[2:3], v7, off offset:-2560
	v_mul_f32_e32 v10, v1, v7
	v_mul_f32_e32 v11, v1, v6
	v_fma_f32 v12, v0, v6, -v10
	v_fma_f32 v13, v0, v7, v11
	v_add_f32_e32 v14, v12, v16
	v_add_f32_e32 v15, v13, v17
	global_store_dword v[2:3], v14, off offset:-2304
	global_store_dword v[2:3], v15, off offset:-2048
	v_mul_f32_e32 v10, v1, v15
	v_mul_f32_e32 v11, v1, v14
	v_fma_f32 v12, v0, v14, -v10
	v_fma_f32 v13, v0, v15, v11
	v_add_f32_e32 v6, v12, v18
	v_add_f32_e32 v7, v13, v19
	global_store_dword v[2:3], v6, off offset:-1792
	global_store_dword v[2:3], v7, off offset:-1536
	v_mul_f32_e32 v10, v1, v7
	v_mul_f32_e32 v11, v1, v6
	v_fma_f32 v12, v0, v6, -v10
	v_fma_f32 v13, v0, v7, v11
	v_add_f32_e32 v14, v12, v20
	v_add_f32_e32 v15, v13, v21
	global_store_dword v[2:3], v14, off offset:-1280
	global_store_dword v[2:3], v15, off offset:-1024
	v_mul_f32_e32 v10, v1, v15
	v_mul_f32_e32 v11, v1, v14
	v_fma_f32 v12, v0, v14, -v10
	v_fma_f32 v13, v0, v15, v11
	v_add_f32_e32 v6, v12, v22
	v_add_f32_e32 v7, v13, v23
	global_store_dword v[2:3], v6, off offset:-768
	global_store_dword v[2:3], v7, off offset:-512
	v_mul_f32_e32 v10, v1, v7
	v_mul_f32_e32 v11, v1, v6
	v_fma_f32 v12, v0, v6, -v10
	v_fma_f32 v13, v0, v7, v11
	v_add_f32_e32 v14, v12, v24
	v_add_f32_e32 v15, v13, v25
	global_store_dword v[2:3], v14, off offset:-256
	global_store_dword v[2:3], v15, off offset:0
	v_mul_f32_e32 v10, v1, v15
	v_mul_f32_e32 v11, v1, v14
	v_fma_f32 v12, v0, v14, -v10
	v_fma_f32 v13, v0, v15, v11
	v_add_f32_e32 v6, v12, v26
	v_add_f32_e32 v7, v13, v27
	global_store_dword v[2:3], v6, off offset:256
	global_store_dword v[2:3], v7, off offset:512
	v_mul_f32_e32 v10, v1, v7
	v_mul_f32_e32 v11, v1, v6
	v_fma_f32 v12, v0, v6, -v10
	v_fma_f32 v13, v0, v7, v11
	v_add_f32_e32 v14, v12, v28
	v_add_f32_e32 v15, v13, v29
	global_store_dword v[2:3], v14, off offset:768
	global_store_dword v[2:3], v15, off offset:1024
	v_mul_f32_e32 v10, v1, v15
	v_mul_f32_e32 v11, v1, v14
	v_fma_f32 v12, v0, v14, -v10
	v_fma_f32 v13, v0, v15, v11
	v_add_f32_e32 v6, v12, v30
	v_add_f32_e32 v7, v13, v31
	global_store_dword v[2:3], v6, off offset:1280
	global_store_dword v[2:3], v7, off offset:1536
	v_mul_f32_e32 v10, v1, v7
	v_mul_f32_e32 v11, v1, v6
	v_fma_f32 v12, v0, v6, -v10
	v_fma_f32 v13, v0, v7, v11
	v_add_f32_e32 v14, v12, v32
	v_add_f32_e32 v15, v13, v33
	global_store_dword v[2:3], v14, off offset:1792
	global_store_dword v[2:3], v15, off offset:2048
	v_mul_f32_e32 v10, v1, v15
	v_mul_f32_e32 v11, v1, v14
	v_fma_f32 v12, v0, v14, -v10
	v_fma_f32 v13, v0, v15, v11
	v_add_f32_e32 v6, v12, v34
	v_add_f32_e32 v7, v13, v35
	global_store_dword v[2:3], v6, off offset:2304
	global_store_dword v[2:3], v7, off offset:2560
	v_mul_f32_e32 v10, v1, v7
	v_mul_f32_e32 v11, v1, v6
	v_fma_f32 v12, v0, v6, -v10
	v_fma_f32 v13, v0, v7, v11
	v_add_f32_e32 v14, v12, v36
	v_add_f32_e32 v15, v13, v37
	global_store_dword v[2:3], v14, off offset:2816
	global_store_dword v[2:3], v15, off offset:3072
	v_mul_f32_e32 v10, v1, v15
	v_mul_f32_e32 v11, v1, v14
	v_fma_f32 v12, v0, v14, -v10
	v_fma_f32 v13, v0, v15, v11
	v_add_f32_e32 v6, v12, v38
	v_add_f32_e32 v7, v13, v39
	s_add_i32 s4, s4, -1
	s_cmp_lg_u32 s4, 0
	s_cbranch_scc1 .Lpfx_loop
	v_lshl_add_u64 v[2:3], v[8:9], 0, s[2:3]
	global_load_dword v16, v[2:3], off offset:-2816
	global_load_dword v17, v[2:3], off offset:-2560
	global_load_dword v18, v[2:3], off offset:-2304
	global_load_dword v19, v[2:3], off offset:-2048
	global_load_dword v20, v[2:3], off offset:-1792
	global_load_dword v21, v[2:3], off offset:-1536
	global_load_dword v22, v[2:3], off offset:-1280
	global_load_dword v23, v[2:3], off offset:-1024
	global_load_dword v24, v[2:3], off offset:-768
	global_load_dword v25, v[2:3], off offset:-512
	global_load_dword v26, v[2:3], off offset:-256
	global_load_dword v27, v[2:3], off offset:0
	global_load_dword v28, v[2:3], off offset:256
	global_load_dword v29, v[2:3], off offset:512
	global_load_dword v30, v[2:3], off offset:768
	global_load_dword v31, v[2:3], off offset:1024
	global_load_dword v32, v[2:3], off offset:1280
	global_load_dword v33, v[2:3], off offset:1536
	global_load_dword v34, v[2:3], off offset:1792
	global_load_dword v35, v[2:3], off offset:2048
	global_load_dword v36, v[2:3], off offset:2304
	global_load_dword v37, v[2:3], off offset:2560
	global_load_dword v38, v[2:3], off offset:2816
	global_load_dword v39, v[2:3], off offset:3072
	s_waitcnt vmcnt(48)
	global_store_dword v[8:9], v6, off offset:-2816
	global_store_dword v[8:9], v7, off offset:-2560
	v_mul_f32_e32 v10, v1, v7
	v_mul_f32_e32 v11, v1, v6
	v_fma_f32 v12, v0, v6, -v10
	v_fma_f32 v13, v0, v7, v11
	v_add_f32_e32 v14, v12, v40
	v_add_f32_e32 v15, v13, v41
	global_store_dword v[8:9], v14, off offset:-2304
	global_store_dword v[8:9], v15, off offset:-2048
	v_mul_f32_e32 v10, v1, v15
	v_mul_f32_e32 v11, v1, v14
	v_fma_f32 v12, v0, v14, -v10
	v_fma_f32 v13, v0, v15, v11
	v_add_f32_e32 v6, v12, v42
	v_add_f32_e32 v7, v13, v43
	global_store_dword v[8:9], v6, off offset:-1792
	global_store_dword v[8:9], v7, off offset:-1536
	v_mul_f32_e32 v10, v1, v7
	v_mul_f32_e32 v11, v1, v6
	v_fma_f32 v12, v0, v6, -v10
	v_fma_f32 v13, v0, v7, v11
	v_add_f32_e32 v14, v12, v44
	v_add_f32_e32 v15, v13, v45
	global_store_dword v[8:9], v14, off offset:-1280
	global_store_dword v[8:9], v15, off offset:-1024
	v_mul_f32_e32 v10, v1, v15
	v_mul_f32_e32 v11, v1, v14
	v_fma_f32 v12, v0, v14, -v10
	v_fma_f32 v13, v0, v15, v11
	v_add_f32_e32 v6, v12, v46
	v_add_f32_e32 v7, v13, v47
	global_store_dword v[8:9], v6, off offset:-768
	global_store_dword v[8:9], v7, off offset:-512
	v_mul_f32_e32 v10, v1, v7
	v_mul_f32_e32 v11, v1, v6
	v_fma_f32 v12, v0, v6, -v10
	v_fma_f32 v13, v0, v7, v11
	v_add_f32_e32 v14, v12, v48
	v_add_f32_e32 v15, v13, v49
	global_store_dword v[8:9], v14, off offset:-256
	global_store_dword v[8:9], v15, off offset:0
	v_mul_f32_e32 v10, v1, v15
	v_mul_f32_e32 v11, v1, v14
	v_fma_f32 v12, v0, v14, -v10
	v_fma_f32 v13, v0, v15, v11
	v_add_f32_e32 v6, v12, v50
	v_add_f32_e32 v7, v13, v51
	global_store_dword v[8:9], v6, off offset:256
	global_store_dword v[8:9], v7, off offset:512
	v_mul_f32_e32 v10, v1, v7
	v_mul_f32_e32 v11, v1, v6
	v_fma_f32 v12, v0, v6, -v10
	v_fma_f32 v13, v0, v7, v11
	v_add_f32_e32 v14, v12, v52
	v_add_f32_e32 v15, v13, v53
	global_store_dword v[8:9], v14, off offset:768
	global_store_dword v[8:9], v15, off offset:1024
	v_mul_f32_e32 v10, v1, v15
	v_mul_f32_e32 v11, v1, v14
	v_fma_f32 v12, v0, v14, -v10
	v_fma_f32 v13, v0, v15, v11
	v_add_f32_e32 v6, v12, v54
	v_add_f32_e32 v7, v13, v55
	global_store_dword v[8:9], v6, off offset:1280
	global_store_dword v[8:9], v7, off offset:1536
	v_mul_f32_e32 v10, v1, v7
	v_mul_f32_e32 v11, v1, v6
	v_fma_f32 v12, v0, v6, -v10
	v_fma_f32 v13, v0, v7, v11
	v_add_f32_e32 v14, v12, v56
	v_add_f32_e32 v15, v13, v57
	global_store_dword v[8:9], v14, off offset:1792
	global_store_dword v[8:9], v15, off offset:2048
	v_mul_f32_e32 v10, v1, v15
	v_mul_f32_e32 v11, v1, v14
	v_fma_f32 v12, v0, v14, -v10
	v_fma_f32 v13, v0, v15, v11
	v_add_f32_e32 v6, v12, v58
	v_add_f32_e32 v7, v13, v59
	global_store_dword v[8:9], v6, off offset:2304
	global_store_dword v[8:9], v7, off offset:2560
	v_mul_f32_e32 v10, v1, v7
	v_mul_f32_e32 v11, v1, v6
	v_fma_f32 v12, v0, v6, -v10
	v_fma_f32 v13, v0, v7, v11
	v_add_f32_e32 v14, v12, v60
	v_add_f32_e32 v15, v13, v61
	global_store_dword v[8:9], v14, off offset:2816
	global_store_dword v[8:9], v15, off offset:3072
	v_mul_f32_e32 v10, v1, v15
	v_mul_f32_e32 v11, v1, v14
	v_fma_f32 v12, v0, v14, -v10
	v_fma_f32 v13, v0, v15, v11
	v_add_f32_e32 v6, v12, v62
	v_add_f32_e32 v7, v13, v63
	s_waitcnt vmcnt(24)
	global_store_dword v[2:3], v6, off offset:-2816
	global_store_dword v[2:3], v7, off offset:-2560
	v_mul_f32_e32 v10, v1, v7
	v_mul_f32_e32 v11, v1, v6
	v_fma_f32 v12, v0, v6, -v10
	v_fma_f32 v13, v0, v7, v11
	v_add_f32_e32 v14, v12, v16
	v_add_f32_e32 v15, v13, v17
	global_store_dword v[2:3], v14, off offset:-2304
	global_store_dword v[2:3], v15, off offset:-2048
	v_mul_f32_e32 v10, v1, v15
	v_mul_f32_e32 v11, v1, v14
	v_fma_f32 v12, v0, v14, -v10
	v_fma_f32 v13, v0, v15, v11
	v_add_f32_e32 v6, v12, v18
	v_add_f32_e32 v7, v13, v19
	global_store_dword v[2:3], v6, off offset:-1792
	global_store_dword v[2:3], v7, off offset:-1536
	v_mul_f32_e32 v10, v1, v7
	v_mul_f32_e32 v11, v1, v6
	v_fma_f32 v12, v0, v6, -v10
	v_fma_f32 v13, v0, v7, v11
	v_add_f32_e32 v14, v12, v20
	v_add_f32_e32 v15, v13, v21
	global_store_dword v[2:3], v14, off offset:-1280
	global_store_dword v[2:3], v15, off offset:-1024
	v_mul_f32_e32 v10, v1, v15
	v_mul_f32_e32 v11, v1, v14
	v_fma_f32 v12, v0, v14, -v10
	v_fma_f32 v13, v0, v15, v11
	v_add_f32_e32 v6, v12, v22
	v_add_f32_e32 v7, v13, v23
	global_store_dword v[2:3], v6, off offset:-768
	global_store_dword v[2:3], v7, off offset:-512
	v_mul_f32_e32 v10, v1, v7
	v_mul_f32_e32 v11, v1, v6
	v_fma_f32 v12, v0, v6, -v10
	v_fma_f32 v13, v0, v7, v11
	v_add_f32_e32 v14, v12, v24
	v_add_f32_e32 v15, v13, v25
	global_store_dword v[2:3], v14, off offset:-256
	global_store_dword v[2:3], v15, off offset:0
	v_mul_f32_e32 v10, v1, v15
	v_mul_f32_e32 v11, v1, v14
	v_fma_f32 v12, v0, v14, -v10
	v_fma_f32 v13, v0, v15, v11
	v_add_f32_e32 v6, v12, v26
	v_add_f32_e32 v7, v13, v27
	global_store_dword v[2:3], v6, off offset:256
	global_store_dword v[2:3], v7, off offset:512
	v_mul_f32_e32 v10, v1, v7
	v_mul_f32_e32 v11, v1, v6
	v_fma_f32 v12, v0, v6, -v10
	v_fma_f32 v13, v0, v7, v11
	v_add_f32_e32 v14, v12, v28
	v_add_f32_e32 v15, v13, v29
	global_store_dword v[2:3], v14, off offset:768
	global_store_dword v[2:3], v15, off offset:1024
	v_mul_f32_e32 v10, v1, v15
	v_mul_f32_e32 v11, v1, v14
	v_fma_f32 v12, v0, v14, -v10
	v_fma_f32 v13, v0, v15, v11
	v_add_f32_e32 v6, v12, v30
	v_add_f32_e32 v7, v13, v31
	global_store_dword v[2:3], v6, off offset:1280
	global_store_dword v[2:3], v7, off offset:1536
	v_mul_f32_e32 v10, v1, v7
	v_mul_f32_e32 v11, v1, v6
	v_fma_f32 v12, v0, v6, -v10
	v_fma_f32 v13, v0, v7, v11
	v_add_f32_e32 v14, v12, v32
	v_add_f32_e32 v15, v13, v33
	global_store_dword v[2:3], v14, off offset:1792
	global_store_dword v[2:3], v15, off offset:2048
	v_mul_f32_e32 v10, v1, v15
	v_mul_f32_e32 v11, v1, v14
	v_fma_f32 v12, v0, v14, -v10
	v_fma_f32 v13, v0, v15, v11
	v_add_f32_e32 v6, v12, v34
	v_add_f32_e32 v7, v13, v35
	global_store_dword v[2:3], v6, off offset:2304
	global_store_dword v[2:3], v7, off offset:2560
	v_mul_f32_e32 v10, v1, v7
	v_mul_f32_e32 v11, v1, v6
	v_fma_f32 v12, v0, v6, -v10
	v_fma_f32 v13, v0, v7, v11
	v_add_f32_e32 v14, v12, v36
	v_add_f32_e32 v15, v13, v37
	global_store_dword v[2:3], v14, off offset:2816
	global_store_dword v[2:3], v15, off offset:3072
	v_mul_f32_e32 v10, v1, v15
	v_mul_f32_e32 v11, v1, v14
	v_fma_f32 v12, v0, v14, -v10
	v_fma_f32 v13, v0, v15, v11
	v_add_f32_e32 v6, v12, v38
	v_add_f32_e32 v7, v13, v39
	.p2align 6
